# st9: rw_mix mix loop reads the hoisted weight registers directly (24 register copies per tile removed), on top of st7
# speedup vs baseline: 1.0099x; 1.0099x over previous
; DI void phase_rw_mix(int layer, int j, int q, LAS unsigned char* lds) {
;     ...
;         __syncthreads();
;         const int c4 = tid & 255, rh = tid >> 8;
;         f32x4 mu0[6], mu1[6];
; #pragma unroll
;         for (int i = 0; i < 6; ++i) { mu0[i] = *(const f32x4*)(mu + (size_t)(i * 2) * D + 4 * c4); mu1[i] = *(const f32x4*)(mu + (size_t)(i * 2 + 1) * D + 4 * c4); }
.LBB0_463:
	s_or_b64 exec, exec, s[14:15]
	s_waitcnt lgkmcnt(0)
	s_barrier
	s_mov_b32 s2, 0
	s_mov_b64 s[14:15], 0
	v_mov_b32_e32 v79, v85
	s_waitcnt vmcnt(0)
	s_branch .LBB0_465

; #define LAS __attribute__((address_space(3)))
; DI unsigned pk2(float lo, float hi) { return f2bf(lo) | (f2bf(hi) << 16); }
; DI void phase_rw_mix(int layer, int j, int q, LAS unsigned char* lds) {
;     ...
;         for (int k = 0; k < 9; ++k) { const int r = rh + 2 * k; if (r >= 17) break;
;             const int t = t0 + r;
;             const f32x4 u = *(const LAS f32x4*)(hs + (r + 1) * 1024 + 4 * c4);
;             f32x4 pv = *(const LAS f32x4*)(hs + r * 1024 + 4 * c4), nx = *(const LAS f32x4*)(hs + (r + 2) * 1024 + 4 * c4);
;             if (t == 0 || t == LC) pv = (f32x4){0.f, 0.f, 0.f, 0.f};
;             if (t == LC - 1 || t == T - 1) nx = (f32x4){0.f, 0.f, 0.f, 0.f};
;             const f32x4 dp = pv - u, dn = nx - u;
; #pragma unroll
;             for (int i = 0; i < 6; ++i) { const f32x4 x = u + mu0[i] * dp + mu1[i] * dn; u32x2 w; w.x = pk2(x[0], x[1]); w.y = pk2(x[2], x[3]);
;                 *(u32x2*)(X + (size_t)i * QROWS * D + (size_t)(lr0 + r) * D + 4 * c4) = w; } }
.LBB0_465:
	v_cmp_gt_i32_e32 vcc, 17, v79
	s_or_b64 s[16:17], s[16:17], exec
	s_and_saveexec_b64 s[18:19], vcc
	s_cbranch_execz .LBB0_464
	v_add_u32_e32 v81, s2, v88
	ds_read_b128 v[90:93], v81 offset:4096
	ds_read_b128 v[94:97], v81
	ds_read_b128 v[98:101], v81 offset:8192
	v_add_u32_e32 v83, s22, v79
	v_and_b32_e32 v81, 0xfffffeff, v83
	v_cmp_ne_u32_e32 vcc, 0, v81
	v_and_b32_e32 v83, 0xffffefff, v83
	s_movk_i32 s3, 0xff
	s_waitcnt lgkmcnt(1)
	v_cndmask_b32_e32 v81, 0, v94, vcc
	v_cndmask_b32_e32 v89, 0, v95, vcc
	v_cndmask_b32_e32 v94, 0, v96, vcc
	v_cndmask_b32_e32 v95, 0, v97, vcc
	v_cmp_ne_u32_e32 vcc, s3, v83
	v_sub_f32_e32 v97, v89, v91
	v_sub_f32_e32 v96, v81, v90
	s_waitcnt lgkmcnt(0)
	v_cndmask_b32_e32 v98, 0, v98, vcc
	v_cndmask_b32_e32 v99, 0, v99, vcc
	v_sub_f32_e32 v99, v99, v91
	v_sub_f32_e32 v98, v98, v90
	v_pk_fma_f32 v[104:105], v[198:199], v[96:97], v[90:91]
	v_cndmask_b32_e32 v83, 0, v100, vcc
	v_pk_fma_f32 v[104:105], v[202:203], v[98:99], v[104:105]
	v_cndmask_b32_e32 v100, 0, v101, vcc
	v_sub_f32_e32 v95, v95, v93
	v_sub_f32_e32 v94, v94, v92
	v_bfe_u32 v81, v104, 16, 1
	v_sub_f32_e32 v101, v100, v93
	v_sub_f32_e32 v100, v83, v92
	v_pk_fma_f32 v[106:107], v[200:201], v[94:95], v[92:93]
	v_add3_u32 v81, v104, v81, s31
	v_bfe_u32 v83, v105, 16, 1
	v_pk_fma_f32 v[106:107], v[204:205], v[100:101], v[106:107]
	v_lshrrev_b32_e32 v81, 16, v81
	v_add3_u32 v83, v105, v83, s31
	v_add_u32_e32 v102, s21, v79
	v_and_or_b32 v104, v83, s0, v81
	v_bfe_u32 v81, v106, 16, 1
	v_ashrrev_i32_e32 v103, 31, v102
	v_add3_u32 v81, v106, v81, s31
	v_bfe_u32 v83, v107, 16, 1
	v_lshlrev_b64 v[102:103], 11, v[102:103]
	v_lshrrev_b32_e32 v81, 16, v81
	v_add3_u32 v83, v107, v83, s31
	v_lshl_add_u64 v[102:103], v[50:51], 0, v[102:103]
	v_and_or_b32 v105, v83, s0, v81
	global_store_dwordx2 v[102:103], v[104:105], off
	v_pk_fma_f32 v[104:105], v[206:207], v[96:97], v[90:91]
	v_pk_fma_f32 v[106:107], v[208:209], v[94:95], v[92:93]
	v_pk_fma_f32 v[104:105], v[210:211], v[98:99], v[104:105]
	v_pk_fma_f32 v[106:107], v[212:213], v[100:101], v[106:107]
	v_bfe_u32 v81, v104, 16, 1
	v_add3_u32 v81, v104, v81, s31
	v_bfe_u32 v83, v105, 16, 1
	v_lshrrev_b32_e32 v81, 16, v81
	v_add3_u32 v83, v105, v83, s31
	v_and_or_b32 v104, v83, s0, v81
	v_bfe_u32 v81, v106, 16, 1
	v_add3_u32 v81, v106, v81, s31
	v_bfe_u32 v83, v107, 16, 1
	s_mov_b32 s3, 0x1100000
	v_lshrrev_b32_e32 v81, 16, v81
	v_add3_u32 v83, v107, v83, s31
	v_add_co_u32_e32 v106, vcc, s3, v102
	v_and_or_b32 v105, v83, s0, v81
	s_nop 0
	v_addc_co_u32_e32 v107, vcc, 0, v103, vcc
	global_store_dwordx2 v[106:107], v[104:105], off
	v_pk_fma_f32 v[104:105], v[214:215], v[96:97], v[90:91]
	v_pk_fma_f32 v[106:107], v[216:217], v[94:95], v[92:93]
	v_pk_fma_f32 v[104:105], v[218:219], v[98:99], v[104:105]
	v_pk_fma_f32 v[106:107], v[220:221], v[100:101], v[106:107]
	v_bfe_u32 v81, v104, 16, 1
	v_add3_u32 v81, v104, v81, s31
	v_bfe_u32 v83, v105, 16, 1
	v_lshrrev_b32_e32 v81, 16, v81
	v_add3_u32 v83, v105, v83, s31
	v_and_or_b32 v104, v83, s0, v81
	v_bfe_u32 v81, v106, 16, 1
	v_add3_u32 v81, v106, v81, s31
	v_bfe_u32 v83, v107, 16, 1
	s_mov_b32 s3, 0x2200000
	v_lshrrev_b32_e32 v81, 16, v81
	v_add3_u32 v83, v107, v83, s31
	v_add_co_u32_e32 v106, vcc, s3, v102
	v_and_or_b32 v105, v83, s0, v81
	s_nop 0
	v_addc_co_u32_e32 v107, vcc, 0, v103, vcc
	global_store_dwordx2 v[106:107], v[104:105], off
	v_pk_fma_f32 v[104:105], v[222:223], v[96:97], v[90:91]
	v_pk_fma_f32 v[106:107], v[224:225], v[94:95], v[92:93]
	v_pk_fma_f32 v[104:105], v[226:227], v[98:99], v[104:105]
	v_pk_fma_f32 v[106:107], v[228:229], v[100:101], v[106:107]
	v_bfe_u32 v81, v104, 16, 1
	v_add3_u32 v81, v104, v81, s31
	v_bfe_u32 v83, v105, 16, 1
	v_lshrrev_b32_e32 v81, 16, v81
	v_add3_u32 v83, v105, v83, s31
	v_and_or_b32 v104, v83, s0, v81
	v_bfe_u32 v81, v106, 16, 1
	v_add3_u32 v81, v106, v81, s31
	v_bfe_u32 v83, v107, 16, 1
	s_mov_b32 s3, 0x3300000
	v_lshrrev_b32_e32 v81, 16, v81
	v_add3_u32 v83, v107, v83, s31
	v_add_co_u32_e32 v106, vcc, s3, v102
	v_and_or_b32 v105, v83, s0, v81
	s_nop 0
	v_addc_co_u32_e32 v107, vcc, 0, v103, vcc
	global_store_dwordx2 v[106:107], v[104:105], off
	v_pk_fma_f32 v[104:105], v[230:231], v[96:97], v[90:91]
	v_pk_fma_f32 v[106:107], v[232:233], v[94:95], v[92:93]
	v_pk_fma_f32 v[104:105], v[236:237], v[98:99], v[104:105]
	v_pk_fma_f32 v[106:107], v[238:239], v[100:101], v[106:107]
	v_bfe_u32 v81, v104, 16, 1
	v_add3_u32 v81, v104, v81, s31
	v_bfe_u32 v83, v105, 16, 1
	v_lshrrev_b32_e32 v81, 16, v81
	v_add3_u32 v83, v105, v83, s31
	v_and_or_b32 v104, v83, s0, v81
	v_bfe_u32 v81, v106, 16, 1
	v_add3_u32 v81, v106, v81, s31
	v_bfe_u32 v83, v107, 16, 1
	v_pk_fma_f32 v[90:91], v[240:241], v[96:97], v[90:91]
	v_lshrrev_b32_e32 v81, 16, v81
	v_add3_u32 v83, v107, v83, s31
	v_pk_fma_f32 v[90:91], v[244:245], v[98:99], v[90:91]
	v_and_or_b32 v105, v83, s0, v81
	v_bfe_u32 v81, v90, 16, 1
	v_pk_fma_f32 v[92:93], v[242:243], v[94:95], v[92:93]
	v_add3_u32 v81, v90, v81, s31
	v_bfe_u32 v83, v91, 16, 1
	s_mov_b32 s3, 0x4400000
	v_pk_fma_f32 v[92:93], v[246:247], v[100:101], v[92:93]
	v_lshrrev_b32_e32 v81, 16, v81
	v_add3_u32 v83, v91, v83, s31
	s_addk_i32 s2, 0x2000
	v_add_co_u32_e32 v106, vcc, s3, v102
	v_and_or_b32 v90, v83, s0, v81
	v_bfe_u32 v81, v92, 16, 1
	s_cmp_eq_u32 s2, 0x12000
	v_addc_co_u32_e32 v107, vcc, 0, v103, vcc
	v_add3_u32 v81, v92, v81, s31
	v_bfe_u32 v83, v93, 16, 1
	s_cselect_b64 s[24:25], -1, 0
	v_lshrrev_b32_e32 v81, 16, v81
	v_add3_u32 v83, v93, v83, s31
	v_add_co_u32_e32 v92, vcc, 0x5500000, v102
	s_andn2_b64 s[16:17], s[16:17], exec
	s_and_b64 s[24:25], s[24:25], exec
	v_and_or_b32 v91, v83, s0, v81
	v_addc_co_u32_e32 v93, vcc, 0, v103, vcc
	v_add_u32_e32 v79, 2, v79
	s_or_b64 s[16:17], s[16:17], s[24:25]
	global_store_dwordx2 v[106:107], v[104:105], off
	global_store_dwordx2 v[92:93], v[90:91], off
	s_branch .LBB0_464
